# P21: phase-0 table loops run by the 208 blocks without a GEMV item (GEMV blocks were the stragglers of the HBM-bound phase)
# speedup vs baseline: 1.0064x; 1.0064x over previous
.LBB0_50:
	s_cmp_lt_u32 s2, 48
	s_cbranch_scc1 .LBB0_79
	s_sub_i32 s2, s2, 48
	s_sub_i32 s3, s3, 48
	s_lshl_b32 s10, s3, 9
	v_cvt_f32_u32_e32 v1, s10
	v_lshl_add_u32 v0, s2, 9, v22
	s_mov_b32 s4, 0x80000
	v_cmp_gt_i32_e32 vcc, s4, v0
	v_rcp_iflag_f32_e32 v8, v1
	v_add_u32_e32 v1, s10, v0
	v_and_b32_e32 v2, 7, v22
	s_and_saveexec_b64 s[8:9], vcc
	s_cbranch_execz .LBB0_58
	v_mul_f32_e32 v5, 0x4f7ffffe, v8
	v_cvt_u32_f32_e32 v5, v5
	v_mov_b32_e32 v4, s10
	v_cmp_gt_i32_e64 s[4:5], s4, v1
	v_max_i32_e32 v3, 0x80000, v1
	s_mov_b64 s[16:17], -1
	v_addc_co_u32_e64 v4, s[6:7], v0, v4, s[4:5]
	s_sub_i32 s6, 0, s10
	v_sub_u32_e32 v3, v3, v4
	v_mul_lo_u32 v4, s6, v5
	v_mul_hi_u32 v4, v5, v4
	v_add_u32_e32 v4, v5, v4
	v_mul_hi_u32 v4, v3, v4
	v_mul_lo_u32 v5, v4, s10
	v_sub_u32_e32 v3, v3, v5
	v_add_u32_e32 v5, 1, v4
	v_cmp_le_u32_e64 s[6:7], s10, v3
	s_nop 1
	v_cndmask_b32_e64 v4, v4, v5, s[6:7]
	v_subrev_u32_e32 v5, s10, v3
	v_cndmask_b32_e64 v3, v3, v5, s[6:7]
	v_add_u32_e32 v5, 1, v4
	v_cmp_le_u32_e64 s[6:7], s10, v3
	s_nop 1
	v_cndmask_b32_e64 v3, v4, v5, s[6:7]
	v_addc_co_u32_e64 v6, s[4:5], 1, v3, s[4:5]
	v_cmp_lt_u32_e64 s[4:5], 1, v6
	v_mov_b32_e32 v4, v0
	s_and_saveexec_b64 s[6:7], s[4:5]
	s_cbranch_execz .LBB0_55
	s_add_u32 s16, s28, 0x1de98000
	s_addc_u32 s17, s29, 0
	v_and_b32_e32 v7, -2, v6
	s_lshl_b32 s11, s3, 10
	v_mov_b32_e32 v3, v2
	s_mov_b32 s20, s11
	s_mov_b64 s[18:19], 0
	v_mov_b32_e32 v9, v7
	v_mov_b64_e32 v[4:5], v[0:1]

.LBB0_78:
	s_add_i32 s2, s2, 48
	s_or_b64 exec, exec, s[4:5]
	s_waitcnt lgkmcnt(0)
	s_barrier
